# attention: drop the compiler's conservative vmcnt(0) in all six softmax loops (counted asm waits cover the tiles) + pipelined reads + max3 tree + setprio + Nyquist rows
# speedup vs baseline: 1.0070x; 1.0070x over previous
.Lprio_2:
	v_add_u32_e32 v101, s4, v96
	v_add_u32_e32 v100, s4, v95
	v_add_u32_e32 v99, s4, v94
	v_add_u32_e32 v98, s4, v93
	ds_read_b128 v[196:199], v101
	ds_read_b128 v[200:203], v100
	ds_read_b128 v[232:235], v101 offset:4096
	ds_read_b128 v[236:239], v100 offset:4096
	ds_read_b128 v[240:243], v99
	s_waitcnt lgkmcnt(4)
	v_mfma_f32_32x32x16_bf16 v[34:49], v[196:199], v[66:69], 0
	ds_read_b128 v[244:247], v99 offset:4096
	s_waitcnt lgkmcnt(4)
	v_mfma_f32_32x32x16_bf16 v[34:49], v[200:203], v[70:73], v[34:49]
	ds_read_b128 v[196:199], v98 offset:4096
	s_waitcnt lgkmcnt(4)
	v_mfma_f32_32x32x16_bf16 v[50:65], v[232:235], v[66:69], 0
	ds_read_b128 v[200:203], v98
	s_waitcnt lgkmcnt(4)
	v_mfma_f32_32x32x16_bf16 v[50:65], v[236:239], v[70:73], v[50:65]
	s_waitcnt lgkmcnt(3)
	v_mfma_f32_32x32x16_bf16 v[34:49], v[240:243], v[74:77], v[34:49]
	s_waitcnt lgkmcnt(2)
	v_mfma_f32_32x32x16_bf16 v[50:65], v[244:247], v[74:77], v[50:65]
	s_waitcnt lgkmcnt(1)
	v_mfma_f32_32x32x16_bf16 v[50:65], v[196:199], v[78:81], v[50:65]
	s_waitcnt lgkmcnt(0)
	v_mfma_f32_32x32x16_bf16 v[34:49], v[200:203], v[78:81], v[34:49]
	v_cmp_gt_u32_e32 vcc, 0x100, v206
	s_setprio 0
	s_cbranch_vccz .Lprio_1
	s_setprio 1

.Lprio_8:
	v_add_u32_e32 v99, s4, v94
	v_add_u32_e32 v98, s4, v93
	v_add_u32_e32 v97, s4, v92
	v_add_u32_e32 v95, s4, v91
	ds_read_b128 v[196:199], v99
	ds_read_b128 v[200:203], v98
	ds_read_b128 v[232:235], v99 offset:4096
	ds_read_b128 v[236:239], v98 offset:4096
	ds_read_b128 v[240:243], v97
	s_waitcnt lgkmcnt(4)
	v_mfma_f32_32x32x16_bf16 v[34:49], v[196:199], v[66:69], 0
	ds_read_b128 v[244:247], v97 offset:4096
	s_waitcnt lgkmcnt(4)
	v_mfma_f32_32x32x16_bf16 v[34:49], v[200:203], v[70:73], v[34:49]
	ds_read_b128 v[196:199], v95 offset:4096
	s_waitcnt lgkmcnt(4)
	v_mfma_f32_32x32x16_bf16 v[50:65], v[232:235], v[66:69], 0
	ds_read_b128 v[200:203], v95
	s_waitcnt lgkmcnt(4)
	v_mfma_f32_32x32x16_bf16 v[50:65], v[236:239], v[70:73], v[50:65]
	s_waitcnt lgkmcnt(3)
	v_mfma_f32_32x32x16_bf16 v[34:49], v[240:243], v[74:77], v[34:49]
	s_waitcnt lgkmcnt(2)
	v_mfma_f32_32x32x16_bf16 v[50:65], v[244:247], v[74:77], v[50:65]
	s_waitcnt lgkmcnt(1)
	v_mfma_f32_32x32x16_bf16 v[50:65], v[196:199], v[78:81], v[50:65]
	s_waitcnt lgkmcnt(0)
	v_mfma_f32_32x32x16_bf16 v[34:49], v[200:203], v[78:81], v[34:49]
	v_cmp_gt_u32_e32 vcc, 0x100, v206
	s_setprio 0
	s_cbranch_vccz .Lprio_7
	s_setprio 1

.Lprio_14:
	s_and_b32 s8, s17, 0xc000
	v_or_b32_e32 v50, s8, v94
	v_or_b32_e32 v204, s8, v95
	v_or_b32_e32 v205, s8, v96
	v_or_b32_e32 v248, s8, v97
	ds_read_b128 v[196:199], v50
	ds_read_b128 v[200:203], v204
	ds_read_b128 v[232:235], v50 offset:4096
	ds_read_b128 v[236:239], v204 offset:4096
	ds_read_b128 v[240:243], v205
	s_andn2_b64 vcc, exec, s[0:1]
	s_waitcnt lgkmcnt(4)
	v_mfma_f32_32x32x16_bf16 v[34:49], v[196:199], v[66:69], 0
	ds_read_b128 v[244:247], v205 offset:4096
	s_waitcnt lgkmcnt(4)
	v_mfma_f32_32x32x16_bf16 v[34:49], v[200:203], v[70:73], v[34:49]
	ds_read_b128 v[196:199], v248
	s_waitcnt lgkmcnt(4)
	v_mfma_f32_32x32x16_bf16 v[50:65], v[232:235], v[66:69], 0
	ds_read_b128 v[200:203], v248 offset:4096
	s_waitcnt lgkmcnt(4)
	v_mfma_f32_32x32x16_bf16 v[50:65], v[236:239], v[70:73], v[50:65]
	s_waitcnt lgkmcnt(3)
	v_mfma_f32_32x32x16_bf16 v[34:49], v[240:243], v[74:77], v[34:49]
	s_waitcnt lgkmcnt(2)
	v_mfma_f32_32x32x16_bf16 v[50:65], v[244:247], v[74:77], v[50:65]
	s_waitcnt lgkmcnt(1)
	v_mfma_f32_32x32x16_bf16 v[34:49], v[196:199], v[78:81], v[34:49]
	s_waitcnt lgkmcnt(0)
	v_mfma_f32_32x32x16_bf16 v[50:65], v[200:203], v[78:81], v[50:65]
	s_nop 1
	s_cbranch_vccnz .LBB0_405
	s_lshl_b32 s0, s54, 6
	s_sub_i32 s1, s9, s10
	s_add_i32 s0, s1, s0
	s_addk_i32 s0, 0xf000
	v_sub_u32_e32 v101, s0, v91
	v_add_u32_e32 v101, 63, v101
	v_subrev_u32_e32 v102, s0, v98
	v_max_i32_e32 v101, v101, v102
	s_movk_i32 s1, 0x80
	v_cmp_lt_i32_e32 vcc, s1, v101
	s_and_saveexec_b64 s[4:5], vcc
	s_cbranch_execz .LBB0_404
	v_add_u32_e32 v101, s0, v99
	s_movk_i32 s0, 0x101
	v_cmp_gt_u32_e32 vcc, s0, v101
	v_add_u32_e32 v102, 0xffffff1f, v101
	s_movk_i32 s0, 0xfefe
	v_cndmask_b32_e32 v34, v215, v34, vcc
	v_cmp_lt_u32_e32 vcc, s0, v102
	v_add_u32_e32 v102, 0xffffff00, v101
	s_nop 0
	v_cndmask_b32_e32 v50, v215, v50, vcc
	v_cmp_lt_u32_e32 vcc, s0, v102
	v_add_u32_e32 v102, 0xffffff20, v101
	s_nop 0
	v_cndmask_b32_e32 v35, v215, v35, vcc
	v_cmp_lt_u32_e32 vcc, s0, v102
	v_add_u32_e32 v102, 0xffffff01, v101
	s_nop 0
	v_cndmask_b32_e32 v51, v215, v51, vcc
	v_cmp_lt_u32_e32 vcc, s0, v102
	v_add_u32_e32 v102, 0xffffff21, v101
	s_nop 0
	v_cndmask_b32_e32 v36, v215, v36, vcc
	v_cmp_lt_u32_e32 vcc, s0, v102
	v_add_u32_e32 v102, 0xffffff02, v101
	s_nop 0
	v_cndmask_b32_e32 v52, v215, v52, vcc
	v_cmp_lt_u32_e32 vcc, s0, v102
	v_add_u32_e32 v102, 0xffffff22, v101
	s_nop 0
	v_cndmask_b32_e32 v37, v215, v37, vcc
	v_cmp_lt_u32_e32 vcc, s0, v102
	v_add_u32_e32 v102, 0xffffff07, v101
	s_nop 0
	v_cndmask_b32_e32 v53, v215, v53, vcc
	v_cmp_lt_u32_e32 vcc, s0, v102
	v_add_u32_e32 v102, 0xffffff27, v101
	s_nop 0
	v_cndmask_b32_e32 v38, v215, v38, vcc
	v_cmp_lt_u32_e32 vcc, s0, v102
	v_add_u32_e32 v102, 0xffffff08, v101
	s_nop 0
	v_cndmask_b32_e32 v54, v215, v54, vcc
	v_cmp_lt_u32_e32 vcc, s0, v102
	v_add_u32_e32 v102, 0xffffff28, v101
	s_nop 0
	v_cndmask_b32_e32 v39, v215, v39, vcc
	v_cmp_lt_u32_e32 vcc, s0, v102
	v_add_u32_e32 v102, 0xffffff09, v101
	s_nop 0
	v_cndmask_b32_e32 v55, v215, v55, vcc
	v_cmp_lt_u32_e32 vcc, s0, v102
	v_add_u32_e32 v102, 0xffffff29, v101
	s_nop 0
	v_cndmask_b32_e32 v40, v215, v40, vcc
	v_cmp_lt_u32_e32 vcc, s0, v102
	v_add_u32_e32 v102, 0xffffff0a, v101
	s_nop 0
	v_cndmask_b32_e32 v56, v215, v56, vcc
	v_cmp_lt_u32_e32 vcc, s0, v102
	v_add_u32_e32 v102, 0xffffff2a, v101
	s_nop 0
	v_cndmask_b32_e32 v41, v215, v41, vcc
	v_cmp_lt_u32_e32 vcc, s0, v102
	v_add_u32_e32 v102, 0xffffff0f, v101
	s_nop 0
	v_cndmask_b32_e32 v57, v215, v57, vcc
	v_cmp_lt_u32_e32 vcc, s0, v102
	v_add_u32_e32 v102, 0xffffff2f, v101
	s_nop 0
	v_cndmask_b32_e32 v42, v215, v42, vcc
	v_cmp_lt_u32_e32 vcc, s0, v102
	v_add_u32_e32 v102, 0xffffff10, v101
	s_nop 0
	v_cndmask_b32_e32 v58, v215, v58, vcc
	v_cmp_lt_u32_e32 vcc, s0, v102
	v_add_u32_e32 v102, 0xffffff30, v101
	s_nop 0
	v_cndmask_b32_e32 v43, v215, v43, vcc
	v_cmp_lt_u32_e32 vcc, s0, v102
	v_add_u32_e32 v102, 0xffffff11, v101
	s_nop 0
	v_cndmask_b32_e32 v59, v215, v59, vcc
	v_cmp_lt_u32_e32 vcc, s0, v102
	v_add_u32_e32 v102, 0xffffff31, v101
	s_nop 0
	v_cndmask_b32_e32 v44, v215, v44, vcc
	v_cmp_lt_u32_e32 vcc, s0, v102
	v_add_u32_e32 v102, 0xffffff12, v101
	s_nop 0
	v_cndmask_b32_e32 v60, v215, v60, vcc
	v_cmp_lt_u32_e32 vcc, s0, v102
	v_add_u32_e32 v102, 0xffffff32, v101
	s_nop 0
	v_cndmask_b32_e32 v45, v215, v45, vcc
	v_cmp_lt_u32_e32 vcc, s0, v102
	v_add_u32_e32 v102, 0xffffff17, v101
	s_nop 0
	v_cndmask_b32_e32 v61, v215, v61, vcc
	v_cmp_lt_u32_e32 vcc, s0, v102
	v_add_u32_e32 v102, 0xffffff37, v101
	s_nop 0
	v_cndmask_b32_e32 v46, v215, v46, vcc
	v_cmp_lt_u32_e32 vcc, s0, v102
	v_add_u32_e32 v102, 0xffffff18, v101
	s_nop 0
	v_cndmask_b32_e32 v62, v215, v62, vcc
	v_cmp_lt_u32_e32 vcc, s0, v102
	v_add_u32_e32 v102, 0xffffff38, v101
	s_nop 0
	v_cndmask_b32_e32 v47, v215, v47, vcc
	v_cmp_lt_u32_e32 vcc, s0, v102
	v_add_u32_e32 v102, 0xffffff19, v101
	s_nop 0
	v_cndmask_b32_e32 v63, v215, v63, vcc
	v_cmp_lt_u32_e32 vcc, s0, v102
	v_add_u32_e32 v102, 0xffffff39, v101
	s_nop 0
	v_cndmask_b32_e32 v48, v215, v48, vcc
	v_cmp_lt_u32_e32 vcc, s0, v102
	v_add_u32_e32 v102, 0xffffff1a, v101
	v_add_u32_e32 v101, 0xffffff3a, v101
	v_cndmask_b32_e32 v64, v215, v64, vcc
	v_cmp_lt_u32_e32 vcc, s0, v102
	s_nop 1
	v_cndmask_b32_e32 v49, v215, v49, vcc
	v_cmp_lt_u32_e32 vcc, s0, v101
	s_nop 1
	v_cndmask_b32_e32 v65, v215, v65, vcc

.Lprio_16:
	s_and_b32 s4, s56, 0xc000
	v_or_b32_e32 v38, s4, v110
	v_or_b32_e32 v204, s4, v111
	v_or_b32_e32 v205, s4, v112
	v_or_b32_e32 v248, s4, v113
	ds_read_b128 v[196:199], v38
	ds_read_b128 v[200:203], v204
	ds_read_b128 v[232:235], v38 offset:4096
	ds_read_b128 v[236:239], v204 offset:4096
	ds_read_b128 v[240:243], v205
	s_andn2_b64 vcc, exec, s[10:11]
	s_waitcnt lgkmcnt(4)
	v_mfma_f32_32x32x16_bf16 v[50:65], v[196:199], v[82:85], 0
	ds_read_b128 v[244:247], v205 offset:4096
	s_waitcnt lgkmcnt(4)
	v_mfma_f32_32x32x16_bf16 v[50:65], v[200:203], v[86:89], v[50:65]
	ds_read_b128 v[196:199], v248
	s_waitcnt lgkmcnt(4)
	v_mfma_f32_32x32x16_bf16 v[34:49], v[232:235], v[82:85], 0
	ds_read_b128 v[200:203], v248 offset:4096
	s_waitcnt lgkmcnt(4)
	v_mfma_f32_32x32x16_bf16 v[34:49], v[236:239], v[86:89], v[34:49]
	s_waitcnt lgkmcnt(3)
	v_mfma_f32_32x32x16_bf16 v[50:65], v[240:243], v[90:93], v[50:65]
	s_waitcnt lgkmcnt(2)
	v_mfma_f32_32x32x16_bf16 v[34:49], v[244:247], v[90:93], v[34:49]
	s_waitcnt lgkmcnt(1)
	v_mfma_f32_32x32x16_bf16 v[50:65], v[196:199], v[94:97], v[50:65]
	s_waitcnt lgkmcnt(0)
	v_mfma_f32_32x32x16_bf16 v[34:49], v[200:203], v[94:97], v[34:49]
	s_nop 1
	s_cbranch_vccnz .LBB0_474
	s_lshl_b32 s0, s5, 6
	s_sub_i32 s1, s54, s57
	s_add_i32 s0, s1, s0
	s_addk_i32 s0, 0xf000
	s_ashr_i32 s0, s0, 6
	v_sub_u32_e32 v66, s0, v105
	s_movk_i32 s0, 0x7c
	v_mul_lo_u32 v66, v66, s0
	v_add_u32_e32 v117, v114, v66
	ds_read_b32 v116, v117 offset:1056
	v_mov_b32_e32 v67, 0xff800000
	v_mov_b32_e32 v66, 0xff800000
	s_and_saveexec_b64 s[0:1], s[40:41]
	s_cbranch_execz .LBB0_443
	ds_read_b32 v66, v117 offset:928
	s_waitcnt lgkmcnt(0)
	v_add_f32_e32 v66, v50, v66
